# v10 + GEMM1 column-tile assignment rotated per round so every workgroup gets a similar mix of activation/plain/transposed epilogues
# speedup vs baseline: 1.0165x; 1.0047x over previous
.LBB0_263:
	s_add_i32 s58, s58, 1
	s_mul_i32 s0, s58, s31
	s_mul_hi_u32 s1, s58, s3
	s_add_i32 s1, s1, s0
	s_mul_i32 s0, s58, s3
	s_add_u32 s14, s0, s2
	s_addc_u32 s15, s1, s7
	v_mov_b64_e32 v[2:3], 0x900
	v_cmp_lt_i64_e64 s[40:41], s[14:15], v[2:3]
	v_mov_b64_e32 v[2:3], 0x8ff
	v_cmp_gt_i64_e32 vcc, s[14:15], v[2:3]
	s_cbranch_vccnz .LBB0_265
	s_ashr_i32 s0, s14, 31
	s_lshr_b32 s0, s0, 29
	s_add_i32 s0, s14, s0
	s_ashr_i32 s1, s0, 3
	s_and_b32 s0, s0, -8
	s_sub_i32 s0, s14, s0
	s_cmp_lt_i32 s0, 0
	s_cselect_b32 s14, s83, 0x120
	s_mul_i32 s0, s0, s14
	s_add_i32 s0, s0, s1
	s_mul_hi_i32 s1, s0, 0x2aaaaaab
	s_lshr_b32 s14, s1, 31
	s_ashr_i32 s1, s1, 4
	s_add_i32 s1, s1, s14
	s_lshl_b32 s14, s1, 3
	s_sub_i32 s15, 0xc0, s14
	s_min_i32 s15, s15, 8
	s_abs_i32 s16, s15
	v_cvt_f32_u32_e32 v2, s16
	s_sub_i32 s35, 0, s16
	s_mulk_i32 s1, 0x60
	s_sub_i32 s0, s0, s1
	v_rcp_iflag_f32_e32 v2, v2
	s_abs_i32 s1, s0
	s_xor_b32 s17, s0, s15
	s_ashr_i32 s17, s17, 31
	v_mul_f32_e32 v2, 0x4f7ffffe, v2
	v_cvt_u32_f32_e32 v2, v2
	s_nop 0
	v_readfirstlane_b32 s38, v2
	s_mul_i32 s35, s35, s38
	s_mul_hi_u32 s35, s38, s35
	s_add_i32 s38, s38, s35
	s_mul_hi_u32 s35, s1, s38
	s_mul_i32 s38, s35, s16
	s_sub_i32 s1, s1, s38
	s_add_i32 s39, s35, 1
	s_sub_i32 s38, s1, s16
	s_cmp_ge_u32 s1, s16
	s_cselect_b32 s35, s39, s35
	s_cselect_b32 s1, s38, s1
	s_add_i32 s38, s35, 1
	s_cmp_ge_u32 s1, s16
	s_cselect_b32 s1, s38, s35
	s_xor_b32 s1, s1, s17
	s_sub_i32 s48, s1, s17
	s_mul_i32 s1, s48, s15
	s_sub_i32 s0, s0, s1
	s_add_i32 s50, s14, s0
	s_lshl_b32 s1, s58, 1
	s_lshr_b32 s1, 0x3a480, s1
	s_add_i32 s1, s1, s48
	s_and_b32 s1, s1, 3
	s_and_b32 s48, s48, -4
	s_or_b32 s48, s48, s1
